# weight converter loops: issue all 8 next-item loads back to back (removed compiler's mid-sequence vmcnt(0)), first-item wait peeled to preheader
# speedup vs baseline: 1.0011x; 1.0011x over previous
.LBB0_43:
	s_lshl_b32 s2, s26, 14
	s_add_i32 s16, s2, 16
	s_lshl_b32 s2, s7, 6
	s_ashr_i32 s3, s2, 31
	s_lshl_b64 s[4:5], s[2:3], 2
	s_add_u32 s7, s14, s4
	s_addc_u32 s17, s15, s5
	s_getpc_b64 s[4:5]
	s_add_u32 s4, s4, CVT_ONES@rel32@lo+4
	s_addc_u32 s5, s5, CVT_ONES@rel32@hi+12
	s_cmp_lg_u64 s[14:15], 0
	s_cselect_b32 s15, s17, s5
	s_cselect_b32 s14, s7, s4
	s_ashr_i32 s4, s25, 31
	s_mul_hi_u32 s5, s33, s25
	s_mul_i32 s4, s33, s4
	s_add_i32 s5, s5, s4
	s_mul_i32 s4, s33, s25
	s_lshl_b64 s[4:5], s[4:5], 1
	s_add_u32 s7, s12, s4
	s_addc_u32 s12, s13, s5
	s_lshl_b64 s[4:5], s[2:3], 1
	s_add_u32 s4, s7, s4
	s_mul_i32 s3, s10, s3
	s_mul_hi_u32 s7, s10, s2
	s_addc_u32 s5, s12, s5
	s_add_i32 s3, s7, s3
	s_mul_i32 s7, s11, s2
	s_add_i32 s3, s3, s7
	s_mul_i32 s2, s10, s2
	s_lshl_b64 s[2:3], s[2:3], 2
	s_add_u32 s8, s8, s2
	s_addc_u32 s9, s9, s3
	s_ashr_i32 s7, s6, 31
	s_lshl_b64 s[2:3], s[6:7], 2
	v_lshrrev_b32_e32 v82, 3, v64
	s_add_u32 s2, s8, s2
	v_mul_u32_u24_e32 v8, s10, v82
	s_addc_u32 s3, s9, s3
	v_and_b32_e32 v41, 7, v65
	v_mov_b32_e32 v81, 0
	v_lshlrev_b32_e32 v80, 2, v8
	v_lshl_add_u64 v[8:9], s[2:3], 0, v[80:81]
	v_lshlrev_b32_e32 v80, 4, v41
	v_lshl_add_u64 v[8:9], v[8:9], 0, v[80:81]
	s_lshl_b64 s[2:3], s[10:11], 5
	v_lshlrev_b32_e32 v4, 5, v41
	v_lshl_add_u64 v[10:11], v[8:9], 0, s[2:3]
	global_load_dwordx4 v[0:3], v4, s[14:15] offset:16
	s_nop 0
	global_load_dwordx4 v[4:7], v4, s[14:15]
	s_nop 0
	global_load_dwordx4 v[36:39], v[8:9], off nt
	s_waitcnt lgkmcnt(0)
	global_load_dwordx4 v[32:35], v[10:11], off nt
	v_lshl_add_u64 v[8:9], v[10:11], 0, s[2:3]
	v_lshl_add_u64 v[10:11], v[8:9], 0, s[2:3]
	global_load_dwordx4 v[28:31], v[8:9], off nt
	global_load_dwordx4 v[24:27], v[10:11], off nt
	v_lshl_add_u64 v[8:9], v[10:11], 0, s[2:3]
	v_lshl_add_u64 v[10:11], v[8:9], 0, s[2:3]
	global_load_dwordx4 v[20:23], v[8:9], off nt
	global_load_dwordx4 v[16:19], v[10:11], off nt
	v_lshl_add_u64 v[8:9], v[10:11], 0, s[2:3]
	global_load_dwordx4 v[12:15], v[8:9], off nt
	v_lshl_add_u64 v[8:9], v[8:9], 0, s[2:3]
	global_load_dwordx4 v[8:11], v[8:9], off nt
	v_lshlrev_b32_e32 v40, 3, v41
	v_lshlrev_b32_e32 v42, 2, v41
	v_lshlrev_b32_e32 v41, 4, v64
	v_lshlrev_b32_e32 v44, 3, v64
	v_and_b32_e32 v41, 0x70, v41
	v_and_b32_e32 v44, 56, v44
	v_add_u32_e32 v41, s16, v41
	v_mul_u32_u24_e32 v43, 0x84, v82
	v_mul_u32_u24_e32 v45, 0x84, v44
	v_lshlrev_b32_e32 v46, 2, v82
	v_or_b32_e32 v84, 8, v82
	v_or_b32_e32 v86, 16, v82
	v_or_b32_e32 v88, 24, v82
	v_add3_u32 v83, s16, v45, v46
	s_mov_b32 s3, 0
	s_movk_i32 s34, 0xa00
	v_lshlrev_b32_e32 v85, 2, v40
	v_lshlrev_b32_e32 v90, 2, v42
	v_add_u32_e32 v87, v41, v43
	v_lshlrev_b32_e32 v92, 1, v44
	s_waitcnt vmcnt(0)
	s_branch .LBB0_45

.LBB0_64:
	s_lshl_b32 s10, s15, 6
	s_ashr_i32 s11, s10, 31
	s_lshl_b64 s[12:13], s[10:11], 2
	s_add_u32 s15, s26, s12
	s_addc_u32 s28, s27, s13
	s_getpc_b64 s[12:13]
	s_add_u32 s12, s12, CVT_ONES@rel32@lo+4
	s_addc_u32 s13, s13, CVT_ONES@rel32@hi+12
	s_cmp_lg_u64 s[26:27], 0
	s_cselect_b32 s12, s15, s12
	s_mul_i32 s15, s24, s11
	s_mul_hi_u32 s26, s24, s10
	s_cselect_b32 s13, s28, s13
	s_add_i32 s15, s26, s15
	s_mul_i32 s26, s25, s10
	s_add_i32 s27, s15, s26
	s_mul_i32 s26, s24, s10
	s_lshl_b64 s[26:27], s[26:27], 2
	s_add_u32 s16, s16, s26
	s_addc_u32 s17, s17, s27
	s_ashr_i32 s15, s14, 31
	s_lshl_b64 s[14:15], s[14:15], 2
	s_add_u32 s14, s16, s14
	v_mul_u32_u24_e32 v48, s24, v82
	s_addc_u32 s15, s17, s15
	v_lshlrev_b32_e32 v80, 2, v48
	v_lshl_add_u64 v[48:49], s[14:15], 0, v[80:81]
	v_mov_b32_e32 v91, v81
	global_load_dwordx4 v[44:47], v85, s[12:13] offset:16
	global_load_dwordx4 v[40:43], v85, s[12:13]
	v_lshl_add_u64 v[48:49], v[48:49], 0, v[90:91]
	s_lshl_b64 s[12:13], s[24:25], 5
	v_lshl_add_u64 v[56:57], v[48:49], 0, s[12:13]
	global_load_dwordx4 v[48:51], v[48:49], off nt
	s_nop 0
	global_load_dwordx4 v[52:55], v[56:57], off nt
	v_lshl_add_u64 v[56:57], v[56:57], 0, s[12:13]
	v_lshl_add_u64 v[64:65], v[56:57], 0, s[12:13]
	global_load_dwordx4 v[56:59], v[56:57], off nt
	s_nop 0
	global_load_dwordx4 v[60:63], v[64:65], off nt
	v_lshl_add_u64 v[64:65], v[64:65], 0, s[12:13]
	v_lshl_add_u64 v[72:73], v[64:65], 0, s[12:13]
	global_load_dwordx4 v[64:67], v[64:65], off nt
	s_nop 0
	global_load_dwordx4 v[68:71], v[72:73], off nt
	v_lshl_add_u64 v[76:77], v[72:73], 0, s[12:13]
	v_mov_b32_e32 v93, v81
	global_load_dwordx4 v[72:75], v[76:77], off nt
	v_lshl_add_u64 v[76:77], v[76:77], 0, s[12:13]
	global_load_dwordx4 v[76:79], v[76:77], off nt
	ds_write2_b32 v87, v36, v37 offset1:1
	ds_write2_b32 v87, v38, v39 offset0:2 offset1:3
	v_add_u32_e32 v38, 0x420, v87
	ds_write2_b32 v38, v32, v33 offset1:1
	v_add_u32_e32 v32, 0x428, v87
	ds_write2_b32 v32, v34, v35 offset1:1
	v_add_u32_e32 v32, 0x840, v87
	ds_write2_b32 v32, v28, v29 offset1:1
	v_add_u32_e32 v28, 0x848, v87
	ds_write2_b32 v28, v30, v31 offset1:1
	v_add_u32_e32 v28, 0xc60, v87
	ds_write2_b32 v28, v24, v25 offset1:1
	v_add_u32_e32 v24, 0xc68, v87
	ds_write2_b32 v24, v26, v27 offset1:1
	v_add_u32_e32 v24, 0x1080, v87
	ds_write2_b32 v24, v20, v21 offset1:1
	v_add_u32_e32 v20, 0x1088, v87
	ds_write2_b32 v20, v22, v23 offset1:1
	v_add_u32_e32 v20, 0x14a0, v87
	ds_write2_b32 v20, v16, v17 offset1:1
	v_add_u32_e32 v16, 0x14a8, v87
	ds_write2_b32 v16, v18, v19 offset1:1
	v_add_u32_e32 v16, 0x18c0, v87
	ds_write2_b32 v16, v12, v13 offset1:1
	v_add_u32_e32 v12, 0x18c8, v87
	ds_write2_b32 v12, v14, v15 offset1:1
	v_add_u32_e32 v12, 0x1ce0, v87
	ds_write2_b32 v12, v8, v9 offset1:1
	v_add_u32_e32 v8, 0x1ce8, v87
	ds_write2_b32 v8, v10, v11 offset1:1
	s_waitcnt lgkmcnt(0)
	ds_read2_b32 v[8:9], v83 offset1:33
	v_lshl_add_u64 v[14:15], s[4:5], 0, v[92:93]
	v_mad_u64_u32 v[16:17], s[4:5], s33, v82, 0
	v_lshl_add_u64 v[16:17], v[16:17], 1, v[14:15]
	s_waitcnt lgkmcnt(0)
	v_mul_f32_e32 v8, v4, v8
	v_mul_f32_e32 v9, v5, v9
	s_nop 1
	v_cvt_pk_bf16_f32 v8, v8, v9
	ds_read2_b32 v[10:11], v83 offset0:66 offset1:99
	s_andn2_b64 vcc, exec, s[6:7]
	s_mov_b64 s[6:7], -1
	s_waitcnt lgkmcnt(0)
	v_mul_f32_e32 v9, v6, v10
	v_mul_f32_e32 v10, v7, v11
	s_nop 1
	v_cvt_pk_bf16_f32 v9, v9, v10
	ds_read2_b32 v[10:11], v83 offset0:132 offset1:165
	s_waitcnt lgkmcnt(0)
	v_mul_f32_e32 v10, v0, v10
	v_mul_f32_e32 v11, v1, v11
	s_nop 1
	v_cvt_pk_bf16_f32 v10, v10, v11
	ds_read2_b32 v[12:13], v83 offset0:198 offset1:231
	s_waitcnt lgkmcnt(0)
	v_mul_f32_e32 v11, v2, v12
	v_mul_f32_e32 v12, v3, v13
	s_nop 1
	v_cvt_pk_bf16_f32 v11, v11, v12
	ds_read2_b32 v[12:13], v83 offset0:8 offset1:41
	global_store_dwordx4 v[16:17], v[8:11], off
	v_mad_u64_u32 v[16:17], s[4:5], s33, v84, 0
	v_lshl_add_u64 v[16:17], v[16:17], 1, v[14:15]
	s_waitcnt lgkmcnt(0)
	v_mul_f32_e32 v8, v4, v12
	v_mul_f32_e32 v9, v5, v13
	s_nop 1
	v_cvt_pk_bf16_f32 v8, v8, v9
	ds_read2_b32 v[10:11], v83 offset0:74 offset1:107
	s_waitcnt lgkmcnt(0)
	v_mul_f32_e32 v9, v6, v10
	v_mul_f32_e32 v10, v7, v11
	s_nop 1
	v_cvt_pk_bf16_f32 v9, v9, v10
	ds_read2_b32 v[10:11], v83 offset0:140 offset1:173
	s_waitcnt lgkmcnt(0)
	v_mul_f32_e32 v10, v0, v10
	v_mul_f32_e32 v11, v1, v11
	s_nop 1
	v_cvt_pk_bf16_f32 v10, v10, v11
	ds_read2_b32 v[12:13], v83 offset0:206 offset1:239
	s_waitcnt lgkmcnt(0)
	v_mul_f32_e32 v11, v2, v12
	v_mul_f32_e32 v12, v3, v13
	s_nop 1
	v_cvt_pk_bf16_f32 v11, v11, v12
	ds_read2_b32 v[12:13], v83 offset0:16 offset1:49
	global_store_dwordx4 v[16:17], v[8:11], off
	v_mad_u64_u32 v[16:17], s[4:5], s33, v86, 0
	v_lshl_add_u64 v[16:17], v[16:17], 1, v[14:15]
	s_waitcnt lgkmcnt(0)
	v_mul_f32_e32 v8, v4, v12
	v_mul_f32_e32 v9, v5, v13
	s_nop 1
	v_cvt_pk_bf16_f32 v8, v8, v9
	ds_read2_b32 v[10:11], v83 offset0:82 offset1:115
	s_waitcnt lgkmcnt(0)
	v_mul_f32_e32 v9, v6, v10
	v_mul_f32_e32 v10, v7, v11
	s_nop 1
	v_cvt_pk_bf16_f32 v9, v9, v10
	ds_read2_b32 v[10:11], v83 offset0:148 offset1:181
	s_waitcnt lgkmcnt(0)
	v_mul_f32_e32 v10, v0, v10
	v_mul_f32_e32 v11, v1, v11
	s_nop 1
	v_cvt_pk_bf16_f32 v10, v10, v11
	ds_read2_b32 v[12:13], v83 offset0:214 offset1:247
	s_waitcnt lgkmcnt(0)
	v_mul_f32_e32 v11, v2, v12
	v_mul_f32_e32 v12, v3, v13
	s_nop 1
	v_cvt_pk_bf16_f32 v11, v11, v12
	ds_read2_b32 v[12:13], v83 offset0:24 offset1:57
	global_store_dwordx4 v[16:17], v[8:11], off
	s_waitcnt lgkmcnt(0)
	v_mul_f32_e32 v4, v4, v12
	v_mul_f32_e32 v5, v5, v13
	s_nop 1
	v_cvt_pk_bf16_f32 v4, v4, v5
	ds_read2_b32 v[8:9], v83 offset0:90 offset1:123
	s_waitcnt lgkmcnt(0)
	v_mul_f32_e32 v5, v6, v8
	v_mul_f32_e32 v6, v7, v9
	s_nop 1
	v_cvt_pk_bf16_f32 v5, v5, v6
	ds_read2_b32 v[6:7], v83 offset0:156 offset1:189
	s_waitcnt lgkmcnt(0)
	v_mul_f32_e32 v0, v0, v6
	v_mul_f32_e32 v1, v1, v7
	s_nop 1
	v_cvt_pk_bf16_f32 v6, v0, v1
	ds_read2_b32 v[0:1], v83 offset0:222 offset1:255
	s_waitcnt lgkmcnt(0)
	v_mul_f32_e32 v0, v2, v0
	v_mul_f32_e32 v1, v3, v1
	s_nop 1
	v_cvt_pk_bf16_f32 v7, v0, v1
	v_mad_u64_u32 v[0:1], s[4:5], s33, v88, 0
	v_lshl_add_u64 v[0:1], v[0:1], 1, v[14:15]
	global_store_dwordx4 v[0:1], v[4:7], off
	s_waitcnt lgkmcnt(0)
	s_cbranch_vccnz .LBB0_44
	s_ashr_i32 s4, s35, 31
	s_mul_hi_u32 s5, s2, s35
	s_mul_i32 s4, s2, s4
	s_add_i32 s5, s5, s4
	s_mul_i32 s4, s2, s35
	s_lshl_b64 s[4:5], s[4:5], 1
	s_add_u32 s6, s8, s4
	s_addc_u32 s7, s9, s5
	s_lshl_b64 s[4:5], s[10:11], 1
	s_add_u32 s4, s6, s4
	s_waitcnt vmcnt(4)
	v_mov_b64_e32 v[0:1], v[44:45]
	v_mov_b64_e32 v[4:5], v[40:41]
	s_addc_u32 s5, s7, s5
	s_mov_b64 s[6:7], 0
	v_mov_b32_e32 v11, v79
	v_mov_b32_e32 v10, v78
	v_mov_b32_e32 v9, v77
	v_mov_b32_e32 v8, v76
	v_mov_b32_e32 v15, v75
	v_mov_b32_e32 v14, v74
	v_mov_b32_e32 v13, v73
	v_mov_b32_e32 v12, v72
	v_mov_b32_e32 v19, v71
	v_mov_b32_e32 v18, v70
	v_mov_b32_e32 v17, v69
	v_mov_b32_e32 v16, v68
	v_mov_b32_e32 v23, v67
	v_mov_b32_e32 v22, v66
	v_mov_b32_e32 v21, v65
	v_mov_b32_e32 v20, v64
	v_mov_b32_e32 v27, v63
	v_mov_b32_e32 v26, v62
	v_mov_b32_e32 v25, v61
	v_mov_b32_e32 v24, v60
	v_mov_b32_e32 v31, v59
	v_mov_b32_e32 v30, v58
	v_mov_b32_e32 v29, v57
	v_mov_b32_e32 v28, v56
	v_mov_b32_e32 v35, v55
	v_mov_b32_e32 v34, v54
	v_mov_b32_e32 v33, v53
	v_mov_b32_e32 v32, v52
	v_mov_b32_e32 v39, v51
	v_mov_b32_e32 v38, v50
	v_mov_b32_e32 v37, v49
	v_mov_b32_e32 v36, v48
	v_mov_b64_e32 v[2:3], v[46:47]
	v_mov_b64_e32 v[6:7], v[42:43]
	s_branch .LBB0_44

.LBB0_149:
	s_lshl_b32 s0, s72, 14
	s_add_i32 s16, s0, 16
	s_lshl_b32 s0, s5, 6
	s_ashr_i32 s1, s0, 31
	s_lshl_b64 s[2:3], s[0:1], 2
	s_add_u32 s5, s12, s2
	s_addc_u32 s17, s13, s3
	s_getpc_b64 s[2:3]
	s_add_u32 s2, s2, CVT_ONES@rel32@lo+4
	s_addc_u32 s3, s3, CVT_ONES@rel32@hi+12
	s_cmp_lg_u64 s[12:13], 0
	s_cselect_b32 s13, s17, s3
	s_cselect_b32 s12, s5, s2
	s_ashr_i32 s2, s25, 31
	s_mul_hi_u32 s3, s34, s25
	s_mul_i32 s2, s34, s2
	s_add_i32 s3, s3, s2
	s_mul_i32 s2, s34, s25
	s_lshl_b64 s[2:3], s[2:3], 1
	s_add_u32 s5, s10, s2
	s_addc_u32 s10, s11, s3
	s_lshl_b64 s[2:3], s[0:1], 1
	s_add_u32 s2, s5, s2
	s_mul_i32 s1, s8, s1
	s_mul_hi_u32 s5, s8, s0
	s_addc_u32 s3, s10, s3
	s_add_i32 s1, s5, s1
	s_mul_i32 s5, s9, s0
	s_add_i32 s1, s1, s5
	s_mul_i32 s0, s8, s0
	s_lshl_b64 s[0:1], s[0:1], 2
	s_add_u32 s6, s6, s0
	s_addc_u32 s7, s7, s1
	s_ashr_i32 s5, s4, 31
	s_lshl_b64 s[0:1], s[4:5], 2
	v_lshrrev_b32_e32 v82, 3, v155
	s_add_u32 s0, s6, s0
	v_mul_u32_u24_e32 v8, s8, v82
	s_addc_u32 s1, s7, s1
	v_and_b32_e32 v41, 7, v157
	v_mov_b32_e32 v81, 0
	v_lshlrev_b32_e32 v80, 2, v8
	v_lshl_add_u64 v[8:9], s[0:1], 0, v[80:81]
	v_lshlrev_b32_e32 v80, 4, v41
	v_lshl_add_u64 v[8:9], v[8:9], 0, v[80:81]
	s_lshl_b64 s[0:1], s[8:9], 5
	v_lshlrev_b32_e32 v4, 5, v41
	v_lshl_add_u64 v[10:11], v[8:9], 0, s[0:1]
	global_load_dwordx4 v[0:3], v4, s[12:13] offset:16
	s_nop 0
	global_load_dwordx4 v[4:7], v4, s[12:13]
	s_nop 0
	global_load_dwordx4 v[36:39], v[8:9], off nt
	global_load_dwordx4 v[32:35], v[10:11], off nt
	v_lshl_add_u64 v[8:9], v[10:11], 0, s[0:1]
	v_lshl_add_u64 v[10:11], v[8:9], 0, s[0:1]
	global_load_dwordx4 v[28:31], v[8:9], off nt
	global_load_dwordx4 v[24:27], v[10:11], off nt
	v_lshl_add_u64 v[8:9], v[10:11], 0, s[0:1]
	v_lshl_add_u64 v[10:11], v[8:9], 0, s[0:1]
	global_load_dwordx4 v[20:23], v[8:9], off nt
	global_load_dwordx4 v[16:19], v[10:11], off nt
	v_lshl_add_u64 v[8:9], v[10:11], 0, s[0:1]
	global_load_dwordx4 v[12:15], v[8:9], off nt
	v_lshl_add_u64 v[8:9], v[8:9], 0, s[0:1]
	global_load_dwordx4 v[8:11], v[8:9], off nt
	v_lshlrev_b32_e32 v40, 3, v41
	v_lshlrev_b32_e32 v42, 2, v41
	v_lshlrev_b32_e32 v41, 4, v155
	v_lshlrev_b32_e32 v44, 3, v155
	v_and_b32_e32 v41, 0x70, v41
	v_and_b32_e32 v44, 56, v44
	v_add_u32_e32 v41, s16, v41
	v_mul_u32_u24_e32 v43, 0x84, v82
	v_mul_u32_u24_e32 v45, 0x84, v44
	v_lshlrev_b32_e32 v46, 2, v82
	v_or_b32_e32 v84, 8, v82
	v_or_b32_e32 v86, 16, v82
	v_or_b32_e32 v88, 24, v82
	v_add3_u32 v83, s16, v45, v46
	s_mov_b32 s1, 0
	s_movk_i32 s35, 0xa00
	v_lshlrev_b32_e32 v85, 2, v40
	v_lshlrev_b32_e32 v90, 2, v42
	v_add_u32_e32 v87, v41, v43
	v_lshlrev_b32_e32 v92, 1, v44
	s_waitcnt vmcnt(0)
	s_branch .LBB0_151

.LBB0_170:
	s_lshl_b32 s8, s13, 6
	s_ashr_i32 s9, s8, 31
	s_lshl_b64 s[10:11], s[8:9], 2
	s_add_u32 s13, s26, s10
	s_addc_u32 s28, s27, s11
	s_getpc_b64 s[10:11]
	s_add_u32 s10, s10, CVT_ONES@rel32@lo+4
	s_addc_u32 s11, s11, CVT_ONES@rel32@hi+12
	s_cmp_lg_u64 s[26:27], 0
	s_cselect_b32 s10, s13, s10
	s_mul_i32 s13, s24, s9
	s_mul_hi_u32 s26, s24, s8
	s_cselect_b32 s11, s28, s11
	s_add_i32 s13, s26, s13
	s_mul_i32 s26, s25, s8
	s_add_i32 s27, s13, s26
	s_mul_i32 s26, s24, s8
	s_lshl_b64 s[26:27], s[26:27], 2
	s_add_u32 s16, s16, s26
	s_addc_u32 s17, s17, s27
	s_ashr_i32 s13, s12, 31
	s_lshl_b64 s[12:13], s[12:13], 2
	s_add_u32 s12, s16, s12
	v_mul_u32_u24_e32 v48, s24, v82
	s_addc_u32 s13, s17, s13
	v_lshlrev_b32_e32 v80, 2, v48
	v_lshl_add_u64 v[48:49], s[12:13], 0, v[80:81]
	v_mov_b32_e32 v91, v81
	global_load_dwordx4 v[44:47], v85, s[10:11] offset:16
	global_load_dwordx4 v[40:43], v85, s[10:11]
	v_lshl_add_u64 v[48:49], v[48:49], 0, v[90:91]
	s_lshl_b64 s[10:11], s[24:25], 5
	v_lshl_add_u64 v[56:57], v[48:49], 0, s[10:11]
	global_load_dwordx4 v[48:51], v[48:49], off nt
	s_nop 0
	global_load_dwordx4 v[52:55], v[56:57], off nt
	v_lshl_add_u64 v[56:57], v[56:57], 0, s[10:11]
	v_lshl_add_u64 v[64:65], v[56:57], 0, s[10:11]
	global_load_dwordx4 v[56:59], v[56:57], off nt
	s_nop 0
	global_load_dwordx4 v[60:63], v[64:65], off nt
	v_lshl_add_u64 v[64:65], v[64:65], 0, s[10:11]
	v_lshl_add_u64 v[72:73], v[64:65], 0, s[10:11]
	global_load_dwordx4 v[64:67], v[64:65], off nt
	s_nop 0
	global_load_dwordx4 v[68:71], v[72:73], off nt
	v_lshl_add_u64 v[76:77], v[72:73], 0, s[10:11]
	v_mov_b32_e32 v93, v81
	global_load_dwordx4 v[72:75], v[76:77], off nt
	v_lshl_add_u64 v[76:77], v[76:77], 0, s[10:11]
	global_load_dwordx4 v[76:79], v[76:77], off nt
	ds_write2_b32 v87, v36, v37 offset1:1
	ds_write2_b32 v87, v38, v39 offset0:2 offset1:3
	v_add_u32_e32 v38, 0x420, v87
	ds_write2_b32 v38, v32, v33 offset1:1
	v_add_u32_e32 v32, 0x428, v87
	ds_write2_b32 v32, v34, v35 offset1:1
	v_add_u32_e32 v32, 0x840, v87
	ds_write2_b32 v32, v28, v29 offset1:1
	v_add_u32_e32 v28, 0x848, v87
	ds_write2_b32 v28, v30, v31 offset1:1
	v_add_u32_e32 v28, 0xc60, v87
	ds_write2_b32 v28, v24, v25 offset1:1
	v_add_u32_e32 v24, 0xc68, v87
	ds_write2_b32 v24, v26, v27 offset1:1
	v_add_u32_e32 v24, 0x1080, v87
	ds_write2_b32 v24, v20, v21 offset1:1
	v_add_u32_e32 v20, 0x1088, v87
	ds_write2_b32 v20, v22, v23 offset1:1
	v_add_u32_e32 v20, 0x14a0, v87
	ds_write2_b32 v20, v16, v17 offset1:1
	v_add_u32_e32 v16, 0x14a8, v87
	ds_write2_b32 v16, v18, v19 offset1:1
	v_add_u32_e32 v16, 0x18c0, v87
	ds_write2_b32 v16, v12, v13 offset1:1
	v_add_u32_e32 v12, 0x18c8, v87
	ds_write2_b32 v12, v14, v15 offset1:1
	v_add_u32_e32 v12, 0x1ce0, v87
	ds_write2_b32 v12, v8, v9 offset1:1
	v_add_u32_e32 v8, 0x1ce8, v87
	ds_write2_b32 v8, v10, v11 offset1:1
	s_waitcnt lgkmcnt(0)
	ds_read2_b32 v[8:9], v83 offset1:33
	v_lshl_add_u64 v[14:15], s[2:3], 0, v[92:93]
	v_mad_u64_u32 v[16:17], s[2:3], s34, v82, 0
	v_lshl_add_u64 v[16:17], v[16:17], 1, v[14:15]
	s_waitcnt lgkmcnt(0)
	v_mul_f32_e32 v8, v4, v8
	v_mul_f32_e32 v9, v5, v9
	s_nop 1
	v_cvt_pk_bf16_f32 v8, v8, v9
	ds_read2_b32 v[10:11], v83 offset0:66 offset1:99
	s_andn2_b64 vcc, exec, s[4:5]
	s_mov_b64 s[4:5], -1
	s_waitcnt lgkmcnt(0)
	v_mul_f32_e32 v9, v6, v10
	v_mul_f32_e32 v10, v7, v11
	s_nop 1
	v_cvt_pk_bf16_f32 v9, v9, v10
	ds_read2_b32 v[10:11], v83 offset0:132 offset1:165
	s_waitcnt lgkmcnt(0)
	v_mul_f32_e32 v10, v0, v10
	v_mul_f32_e32 v11, v1, v11
	s_nop 1
	v_cvt_pk_bf16_f32 v10, v10, v11
	ds_read2_b32 v[12:13], v83 offset0:198 offset1:231
	s_waitcnt lgkmcnt(0)
	v_mul_f32_e32 v11, v2, v12
	v_mul_f32_e32 v12, v3, v13
	s_nop 1
	v_cvt_pk_bf16_f32 v11, v11, v12
	ds_read2_b32 v[12:13], v83 offset0:8 offset1:41
	global_store_dwordx4 v[16:17], v[8:11], off
	v_mad_u64_u32 v[16:17], s[2:3], s34, v84, 0
	v_lshl_add_u64 v[16:17], v[16:17], 1, v[14:15]
	s_waitcnt lgkmcnt(0)
	v_mul_f32_e32 v8, v4, v12
	v_mul_f32_e32 v9, v5, v13
	s_nop 1
	v_cvt_pk_bf16_f32 v8, v8, v9
	ds_read2_b32 v[10:11], v83 offset0:74 offset1:107
	s_waitcnt lgkmcnt(0)
	v_mul_f32_e32 v9, v6, v10
	v_mul_f32_e32 v10, v7, v11
	s_nop 1
	v_cvt_pk_bf16_f32 v9, v9, v10
	ds_read2_b32 v[10:11], v83 offset0:140 offset1:173
	s_waitcnt lgkmcnt(0)
	v_mul_f32_e32 v10, v0, v10
	v_mul_f32_e32 v11, v1, v11
	s_nop 1
	v_cvt_pk_bf16_f32 v10, v10, v11
	ds_read2_b32 v[12:13], v83 offset0:206 offset1:239
	s_waitcnt lgkmcnt(0)
	v_mul_f32_e32 v11, v2, v12
	v_mul_f32_e32 v12, v3, v13
	s_nop 1
	v_cvt_pk_bf16_f32 v11, v11, v12
	ds_read2_b32 v[12:13], v83 offset0:16 offset1:49
	global_store_dwordx4 v[16:17], v[8:11], off
	v_mad_u64_u32 v[16:17], s[2:3], s34, v86, 0
	v_lshl_add_u64 v[16:17], v[16:17], 1, v[14:15]
	s_waitcnt lgkmcnt(0)
	v_mul_f32_e32 v8, v4, v12
	v_mul_f32_e32 v9, v5, v13
	s_nop 1
	v_cvt_pk_bf16_f32 v8, v8, v9
	ds_read2_b32 v[10:11], v83 offset0:82 offset1:115
	s_waitcnt lgkmcnt(0)
	v_mul_f32_e32 v9, v6, v10
	v_mul_f32_e32 v10, v7, v11
	s_nop 1
	v_cvt_pk_bf16_f32 v9, v9, v10
	ds_read2_b32 v[10:11], v83 offset0:148 offset1:181
	s_waitcnt lgkmcnt(0)
	v_mul_f32_e32 v10, v0, v10
	v_mul_f32_e32 v11, v1, v11
	s_nop 1
	v_cvt_pk_bf16_f32 v10, v10, v11
	ds_read2_b32 v[12:13], v83 offset0:214 offset1:247
	s_waitcnt lgkmcnt(0)
	v_mul_f32_e32 v11, v2, v12
	v_mul_f32_e32 v12, v3, v13
	s_nop 1
	v_cvt_pk_bf16_f32 v11, v11, v12
	ds_read2_b32 v[12:13], v83 offset0:24 offset1:57
	global_store_dwordx4 v[16:17], v[8:11], off
	s_waitcnt lgkmcnt(0)
	v_mul_f32_e32 v4, v4, v12
	v_mul_f32_e32 v5, v5, v13
	s_nop 1
	v_cvt_pk_bf16_f32 v4, v4, v5
	ds_read2_b32 v[8:9], v83 offset0:90 offset1:123
	s_waitcnt lgkmcnt(0)
	v_mul_f32_e32 v5, v6, v8
	v_mul_f32_e32 v6, v7, v9
	s_nop 1
	v_cvt_pk_bf16_f32 v5, v5, v6
	ds_read2_b32 v[6:7], v83 offset0:156 offset1:189
	s_waitcnt lgkmcnt(0)
	v_mul_f32_e32 v0, v0, v6
	v_mul_f32_e32 v1, v1, v7
	s_nop 1
	v_cvt_pk_bf16_f32 v6, v0, v1
	ds_read2_b32 v[0:1], v83 offset0:222 offset1:255
	s_waitcnt lgkmcnt(0)
	v_mul_f32_e32 v0, v2, v0
	v_mul_f32_e32 v1, v3, v1
	s_nop 1
	v_cvt_pk_bf16_f32 v7, v0, v1
	v_mad_u64_u32 v[0:1], s[2:3], s34, v88, 0
	v_lshl_add_u64 v[0:1], v[0:1], 1, v[14:15]
	global_store_dwordx4 v[0:1], v[4:7], off
	s_waitcnt lgkmcnt(0)
	s_cbranch_vccnz .LBB0_150
	s_ashr_i32 s2, s52, 31
	s_mul_hi_u32 s3, s0, s52
	s_mul_i32 s2, s0, s2
	s_add_i32 s3, s3, s2
	s_mul_i32 s2, s0, s52
	s_lshl_b64 s[2:3], s[2:3], 1
	s_add_u32 s4, s6, s2
	s_addc_u32 s5, s7, s3
	s_lshl_b64 s[2:3], s[8:9], 1
	s_add_u32 s2, s4, s2
	s_waitcnt vmcnt(4)
	v_mov_b64_e32 v[0:1], v[44:45]
	v_mov_b64_e32 v[4:5], v[40:41]
	s_addc_u32 s3, s5, s3
	s_mov_b64 s[4:5], 0
	v_mov_b32_e32 v11, v79
	v_mov_b32_e32 v10, v78
	v_mov_b32_e32 v9, v77
	v_mov_b32_e32 v8, v76
	v_mov_b32_e32 v15, v75
	v_mov_b32_e32 v14, v74
	v_mov_b32_e32 v13, v73
	v_mov_b32_e32 v12, v72
	v_mov_b32_e32 v19, v71
	v_mov_b32_e32 v18, v70
	v_mov_b32_e32 v17, v69
	v_mov_b32_e32 v16, v68
	v_mov_b32_e32 v23, v67
	v_mov_b32_e32 v22, v66
	v_mov_b32_e32 v21, v65
	v_mov_b32_e32 v20, v64
	v_mov_b32_e32 v27, v63
	v_mov_b32_e32 v26, v62
	v_mov_b32_e32 v25, v61
	v_mov_b32_e32 v24, v60
	v_mov_b32_e32 v31, v59
	v_mov_b32_e32 v30, v58
	v_mov_b32_e32 v29, v57
	v_mov_b32_e32 v28, v56
	v_mov_b32_e32 v35, v55
	v_mov_b32_e32 v34, v54
	v_mov_b32_e32 v33, v53
	v_mov_b32_e32 v32, v52
	v_mov_b32_e32 v39, v51
	v_mov_b32_e32 v38, v50
	v_mov_b32_e32 v37, v49
	v_mov_b32_e32 v36, v48
	v_mov_b64_e32 v[2:3], v[46:47]
	v_mov_b64_e32 v[6:7], v[42:43]
	s_branch .LBB0_150
.LBB0_172:
	s_mov_b64 s[24:25], 0x800
	s_movk_i32 s0, 0x1600
	s_mov_b64 s[26:27], 0
	s_mov_b32 s52, s12
	s_andn2_b64 vcc, exec, s[28:29]
	s_cbranch_vccz .LBB0_159
	s_branch .LBB0_160
.LBB0_173:
	s_waitcnt vmcnt(0)
	s_barrier
.LBB0_174:
	v_mov_b32_e32 v11, v183
	s_cmpk_lt_i32 s20, 0x672
	s_cselect_b64 s[0:1], -1, 0
	s_cmpk_gt_i32 s20, 0x671
	v_readfirstlane_b32 s6, v11
	s_cbranch_scc1 .LBB0_180
	s_ashr_i32 s2, s20, 31
	s_lshr_b32 s2, s2, 29
	s_add_i32 s4, s20, s2
	s_and_b32 s2, s4, -8
	s_sub_i32 s5, s20, s2
	s_cmp_gt_i32 s5, 1
	s_cbranch_scc0 .LBB0_177
	s_mul_i32 s2, s5, 0xce
	s_add_i32 s7, s2, 2
	s_cbranch_execz .LBB0_178
	s_branch .LBB0_179

.LBB0_341:
	s_lshl_b32 s0, s72, 14
	s_add_i32 s14, s0, 16
	s_lshl_b32 s0, s5, 6
	s_ashr_i32 s1, s0, 31
	s_lshl_b64 s[2:3], s[0:1], 2
	s_add_u32 s5, s12, s2
	s_addc_u32 s15, s13, s3
	s_getpc_b64 s[2:3]
	s_add_u32 s2, s2, CVT_ONES@rel32@lo+4
	s_addc_u32 s3, s3, CVT_ONES@rel32@hi+12
	s_cmp_lg_u64 s[12:13], 0
	s_cselect_b32 s13, s15, s3
	s_cselect_b32 s12, s5, s2
	s_ashr_i32 s2, s17, 31
	s_mul_hi_u32 s3, s28, s17
	s_mul_i32 s2, s28, s2
	s_add_i32 s3, s3, s2
	s_mul_i32 s2, s28, s17
	s_lshl_b64 s[2:3], s[2:3], 1
	s_add_u32 s5, s10, s2
	s_addc_u32 s10, s11, s3
	s_lshl_b64 s[2:3], s[0:1], 1
	s_add_u32 s2, s5, s2
	s_mul_i32 s1, s8, s1
	s_mul_hi_u32 s5, s8, s0
	s_addc_u32 s3, s10, s3
	s_add_i32 s1, s5, s1
	s_mul_i32 s5, s9, s0
	s_add_i32 s1, s1, s5
	s_mul_i32 s0, s8, s0
	s_lshl_b64 s[0:1], s[0:1], 2
	s_add_u32 s6, s6, s0
	s_addc_u32 s7, s7, s1
	s_ashr_i32 s5, s4, 31
	s_lshl_b64 s[0:1], s[4:5], 2
	v_lshrrev_b32_e32 v82, 3, v155
	s_add_u32 s0, s6, s0
	v_mul_u32_u24_e32 v8, s8, v82
	s_addc_u32 s1, s7, s1
	v_and_b32_e32 v41, 7, v157
	v_mov_b32_e32 v81, 0
	v_lshlrev_b32_e32 v80, 2, v8
	v_lshl_add_u64 v[8:9], s[0:1], 0, v[80:81]
	v_lshlrev_b32_e32 v80, 4, v41
	v_lshl_add_u64 v[8:9], v[8:9], 0, v[80:81]
	s_lshl_b64 s[0:1], s[8:9], 5
	v_lshlrev_b32_e32 v4, 5, v41
	v_lshl_add_u64 v[10:11], v[8:9], 0, s[0:1]
	global_load_dwordx4 v[0:3], v4, s[12:13] offset:16
	s_nop 0
	global_load_dwordx4 v[4:7], v4, s[12:13]
	s_nop 0
	global_load_dwordx4 v[36:39], v[8:9], off nt
	global_load_dwordx4 v[32:35], v[10:11], off nt
	v_lshl_add_u64 v[8:9], v[10:11], 0, s[0:1]
	v_lshl_add_u64 v[10:11], v[8:9], 0, s[0:1]
	global_load_dwordx4 v[28:31], v[8:9], off nt
	global_load_dwordx4 v[24:27], v[10:11], off nt
	v_lshl_add_u64 v[8:9], v[10:11], 0, s[0:1]
	v_lshl_add_u64 v[10:11], v[8:9], 0, s[0:1]
	global_load_dwordx4 v[20:23], v[8:9], off nt
	global_load_dwordx4 v[16:19], v[10:11], off nt
	v_lshl_add_u64 v[8:9], v[10:11], 0, s[0:1]
	global_load_dwordx4 v[12:15], v[8:9], off nt
	v_lshl_add_u64 v[8:9], v[8:9], 0, s[0:1]
	global_load_dwordx4 v[8:11], v[8:9], off nt
	v_lshlrev_b32_e32 v40, 3, v41
	v_lshlrev_b32_e32 v42, 2, v41
	v_lshlrev_b32_e32 v41, 4, v155
	v_lshlrev_b32_e32 v44, 3, v155
	v_and_b32_e32 v41, 0x70, v41
	v_and_b32_e32 v44, 56, v44
	v_add_u32_e32 v41, s14, v41
	v_mul_u32_u24_e32 v43, 0x84, v82
	v_mul_u32_u24_e32 v45, 0x84, v44
	v_lshlrev_b32_e32 v46, 2, v82
	v_or_b32_e32 v84, 8, v82
	v_or_b32_e32 v86, 16, v82
	v_or_b32_e32 v88, 24, v82
	v_add3_u32 v83, s14, v45, v46
	s_mov_b32 s1, 0
	s_movk_i32 s29, 0xa00
	v_lshlrev_b32_e32 v85, 2, v40
	v_lshlrev_b32_e32 v90, 2, v42
	v_add_u32_e32 v87, v41, v43
	v_lshlrev_b32_e32 v92, 1, v44
	s_waitcnt vmcnt(0)
	s_branch .LBB0_343

.LBB0_362:
	s_lshl_b32 s8, s13, 6
	s_ashr_i32 s9, s8, 31
	s_lshl_b64 s[10:11], s[8:9], 2
	s_add_u32 s13, s24, s10
	s_addc_u32 s26, s25, s11
	s_getpc_b64 s[10:11]
	s_add_u32 s10, s10, CVT_ONES@rel32@lo+4
	s_addc_u32 s11, s11, CVT_ONES@rel32@hi+12
	s_cmp_lg_u64 s[24:25], 0
	s_cselect_b32 s10, s13, s10
	s_mul_i32 s13, s16, s9
	s_mul_hi_u32 s24, s16, s8
	s_cselect_b32 s11, s26, s11
	s_add_i32 s13, s24, s13
	s_mul_i32 s24, s17, s8
	s_add_i32 s25, s13, s24
	s_mul_i32 s24, s16, s8
	s_lshl_b64 s[24:25], s[24:25], 2
	s_add_u32 s14, s14, s24
	s_addc_u32 s15, s15, s25
	s_ashr_i32 s13, s12, 31
	s_lshl_b64 s[12:13], s[12:13], 2
	s_add_u32 s12, s14, s12
	v_mul_u32_u24_e32 v48, s16, v82
	s_addc_u32 s13, s15, s13
	v_lshlrev_b32_e32 v80, 2, v48
	v_lshl_add_u64 v[48:49], s[12:13], 0, v[80:81]
	v_mov_b32_e32 v91, v81
	global_load_dwordx4 v[44:47], v85, s[10:11] offset:16
	global_load_dwordx4 v[40:43], v85, s[10:11]
	v_lshl_add_u64 v[48:49], v[48:49], 0, v[90:91]
	s_lshl_b64 s[10:11], s[16:17], 5
	v_lshl_add_u64 v[56:57], v[48:49], 0, s[10:11]
	global_load_dwordx4 v[48:51], v[48:49], off nt
	s_nop 0
	global_load_dwordx4 v[52:55], v[56:57], off nt
	v_lshl_add_u64 v[56:57], v[56:57], 0, s[10:11]
	v_lshl_add_u64 v[64:65], v[56:57], 0, s[10:11]
	global_load_dwordx4 v[56:59], v[56:57], off nt
	s_nop 0
	global_load_dwordx4 v[60:63], v[64:65], off nt
	v_lshl_add_u64 v[64:65], v[64:65], 0, s[10:11]
	v_lshl_add_u64 v[72:73], v[64:65], 0, s[10:11]
	v_lshl_add_u64 v[76:77], v[72:73], 0, s[10:11]
	global_load_dwordx4 v[64:67], v[64:65], off nt
	s_nop 0
	global_load_dwordx4 v[68:71], v[72:73], off nt
	v_mov_b32_e32 v93, v81
	global_load_dwordx4 v[72:75], v[76:77], off nt
	v_lshl_add_u64 v[76:77], v[76:77], 0, s[10:11]
	global_load_dwordx4 v[76:79], v[76:77], off nt
	ds_write2_b32 v87, v36, v37 offset1:1
	ds_write2_b32 v87, v38, v39 offset0:2 offset1:3
	v_add_u32_e32 v36, 0x420, v87
	ds_write2_b32 v36, v32, v33 offset1:1
	v_add_u32_e32 v32, 0x428, v87
	ds_write2_b32 v32, v34, v35 offset1:1
	v_add_u32_e32 v32, 0x840, v87
	ds_write2_b32 v32, v28, v29 offset1:1
	v_add_u32_e32 v28, 0x848, v87
	ds_write2_b32 v28, v30, v31 offset1:1
	v_add_u32_e32 v28, 0xc60, v87
	ds_write2_b32 v28, v24, v25 offset1:1
	v_add_u32_e32 v24, 0xc68, v87
	ds_write2_b32 v24, v26, v27 offset1:1
	v_add_u32_e32 v24, 0x1080, v87
	ds_write2_b32 v24, v20, v21 offset1:1
	v_add_u32_e32 v20, 0x1088, v87
	ds_write2_b32 v20, v22, v23 offset1:1
	v_add_u32_e32 v20, 0x14a0, v87
	ds_write2_b32 v20, v16, v17 offset1:1
	v_add_u32_e32 v16, 0x14a8, v87
	ds_write2_b32 v16, v18, v19 offset1:1
	v_add_u32_e32 v16, 0x18c0, v87
	ds_write2_b32 v16, v12, v13 offset1:1
	v_add_u32_e32 v12, 0x18c8, v87
	ds_write2_b32 v12, v14, v15 offset1:1
	v_add_u32_e32 v12, 0x1ce0, v87
	ds_write2_b32 v12, v8, v9 offset1:1
	v_add_u32_e32 v8, 0x1ce8, v87
	ds_write2_b32 v8, v10, v11 offset1:1
	s_waitcnt lgkmcnt(0)
	ds_read2_b32 v[8:9], v83 offset1:33
	v_lshl_add_u64 v[14:15], s[2:3], 0, v[92:93]
	v_mad_u64_u32 v[16:17], s[2:3], s28, v82, 0
	v_lshl_add_u64 v[16:17], v[16:17], 1, v[14:15]
	s_waitcnt lgkmcnt(0)
	v_mul_f32_e32 v8, v4, v8
	v_mul_f32_e32 v9, v5, v9
	s_nop 1
	v_cvt_pk_bf16_f32 v8, v8, v9
	ds_read2_b32 v[10:11], v83 offset0:66 offset1:99
	s_andn2_b64 vcc, exec, s[4:5]
	s_mov_b64 s[4:5], -1
	s_waitcnt lgkmcnt(0)
	v_mul_f32_e32 v9, v6, v10
	v_mul_f32_e32 v10, v7, v11
	s_nop 1
	v_cvt_pk_bf16_f32 v9, v9, v10
	ds_read2_b32 v[10:11], v83 offset0:132 offset1:165
	s_waitcnt lgkmcnt(0)
	v_mul_f32_e32 v10, v0, v10
	v_mul_f32_e32 v11, v1, v11
	s_nop 1
	v_cvt_pk_bf16_f32 v10, v10, v11
	ds_read2_b32 v[12:13], v83 offset0:198 offset1:231
	s_waitcnt lgkmcnt(0)
	v_mul_f32_e32 v11, v2, v12
	v_mul_f32_e32 v12, v3, v13
	s_nop 1
	v_cvt_pk_bf16_f32 v11, v11, v12
	ds_read2_b32 v[12:13], v83 offset0:8 offset1:41
	global_store_dwordx4 v[16:17], v[8:11], off
	v_mad_u64_u32 v[16:17], s[2:3], s28, v84, 0
	v_lshl_add_u64 v[16:17], v[16:17], 1, v[14:15]
	s_waitcnt lgkmcnt(0)
	v_mul_f32_e32 v8, v4, v12
	v_mul_f32_e32 v9, v5, v13
	s_nop 1
	v_cvt_pk_bf16_f32 v8, v8, v9
	ds_read2_b32 v[10:11], v83 offset0:74 offset1:107
	s_waitcnt lgkmcnt(0)
	v_mul_f32_e32 v9, v6, v10
	v_mul_f32_e32 v10, v7, v11
	s_nop 1
	v_cvt_pk_bf16_f32 v9, v9, v10
	ds_read2_b32 v[10:11], v83 offset0:140 offset1:173
	s_waitcnt lgkmcnt(0)
	v_mul_f32_e32 v10, v0, v10
	v_mul_f32_e32 v11, v1, v11
	s_nop 1
	v_cvt_pk_bf16_f32 v10, v10, v11
	ds_read2_b32 v[12:13], v83 offset0:206 offset1:239
	s_waitcnt lgkmcnt(0)
	v_mul_f32_e32 v11, v2, v12
	v_mul_f32_e32 v12, v3, v13
	s_nop 1
	v_cvt_pk_bf16_f32 v11, v11, v12
	ds_read2_b32 v[12:13], v83 offset0:16 offset1:49
	global_store_dwordx4 v[16:17], v[8:11], off
	v_mad_u64_u32 v[16:17], s[2:3], s28, v86, 0
	v_lshl_add_u64 v[16:17], v[16:17], 1, v[14:15]
	s_waitcnt lgkmcnt(0)
	v_mul_f32_e32 v8, v4, v12
	v_mul_f32_e32 v9, v5, v13
	s_nop 1
	v_cvt_pk_bf16_f32 v8, v8, v9
	ds_read2_b32 v[10:11], v83 offset0:82 offset1:115
	s_waitcnt lgkmcnt(0)
	v_mul_f32_e32 v9, v6, v10
	v_mul_f32_e32 v10, v7, v11
	s_nop 1
	v_cvt_pk_bf16_f32 v9, v9, v10
	ds_read2_b32 v[10:11], v83 offset0:148 offset1:181
	s_waitcnt lgkmcnt(0)
	v_mul_f32_e32 v10, v0, v10
	v_mul_f32_e32 v11, v1, v11
	s_nop 1
	v_cvt_pk_bf16_f32 v10, v10, v11
	ds_read2_b32 v[12:13], v83 offset0:214 offset1:247
	s_waitcnt lgkmcnt(0)
	v_mul_f32_e32 v11, v2, v12
	v_mul_f32_e32 v12, v3, v13
	s_nop 1
	v_cvt_pk_bf16_f32 v11, v11, v12
	ds_read2_b32 v[12:13], v83 offset0:24 offset1:57
	global_store_dwordx4 v[16:17], v[8:11], off
	s_waitcnt lgkmcnt(0)
	v_mul_f32_e32 v4, v4, v12
	v_mul_f32_e32 v5, v5, v13
	s_nop 1
	v_cvt_pk_bf16_f32 v4, v4, v5
	ds_read2_b32 v[8:9], v83 offset0:90 offset1:123
	s_waitcnt lgkmcnt(0)
	v_mul_f32_e32 v5, v6, v8
	v_mul_f32_e32 v6, v7, v9
	s_nop 1
	v_cvt_pk_bf16_f32 v5, v5, v6
	ds_read2_b32 v[6:7], v83 offset0:156 offset1:189
	s_waitcnt lgkmcnt(0)
	v_mul_f32_e32 v0, v0, v6
	v_mul_f32_e32 v1, v1, v7
	s_nop 1
	v_cvt_pk_bf16_f32 v6, v0, v1
	ds_read2_b32 v[0:1], v83 offset0:222 offset1:255
	s_waitcnt lgkmcnt(0)
	v_mul_f32_e32 v0, v2, v0
	v_mul_f32_e32 v1, v3, v1
	s_nop 1
	v_cvt_pk_bf16_f32 v7, v0, v1
	v_mad_u64_u32 v[0:1], s[2:3], s28, v88, 0
	v_lshl_add_u64 v[0:1], v[0:1], 1, v[14:15]
	global_store_dwordx4 v[0:1], v[4:7], off
	s_waitcnt lgkmcnt(0)
	s_cbranch_vccnz .LBB0_342
	s_ashr_i32 s2, s34, 31
	s_mul_hi_u32 s3, s0, s34
	s_mul_i32 s2, s0, s2
	s_add_i32 s3, s3, s2
	s_mul_i32 s2, s0, s34
	s_lshl_b64 s[2:3], s[2:3], 1
	s_add_u32 s4, s6, s2
	s_addc_u32 s5, s7, s3
	s_lshl_b64 s[2:3], s[8:9], 1
	s_add_u32 s2, s4, s2
	s_waitcnt vmcnt(4)
	v_mov_b64_e32 v[0:1], v[44:45]
	v_mov_b64_e32 v[4:5], v[40:41]
	s_addc_u32 s3, s5, s3
	s_mov_b64 s[4:5], 0
	v_mov_b32_e32 v11, v79
	v_mov_b32_e32 v10, v78
	v_mov_b32_e32 v9, v77
	v_mov_b32_e32 v8, v76
	v_mov_b32_e32 v15, v75
	v_mov_b32_e32 v14, v74
	v_mov_b32_e32 v13, v73
	v_mov_b32_e32 v12, v72
	v_mov_b32_e32 v19, v71
	v_mov_b32_e32 v18, v70
	v_mov_b32_e32 v17, v69
	v_mov_b32_e32 v16, v68
	v_mov_b32_e32 v23, v67
	v_mov_b32_e32 v22, v66
	v_mov_b32_e32 v21, v65
	v_mov_b32_e32 v20, v64
	v_mov_b32_e32 v27, v63
	v_mov_b32_e32 v26, v62
	v_mov_b32_e32 v25, v61
	v_mov_b32_e32 v24, v60
	v_mov_b32_e32 v31, v59
	v_mov_b32_e32 v30, v58
	v_mov_b32_e32 v29, v57
	v_mov_b32_e32 v28, v56
	v_mov_b32_e32 v35, v55
	v_mov_b32_e32 v34, v54
	v_mov_b32_e32 v33, v53
	v_mov_b32_e32 v32, v52
	v_mov_b32_e32 v39, v51
	v_mov_b32_e32 v38, v50
	v_mov_b32_e32 v37, v49
	v_mov_b32_e32 v36, v48
	v_mov_b64_e32 v[2:3], v[46:47]
	v_mov_b64_e32 v[6:7], v[42:43]
	s_branch .LBB0_342
